# A-layer mixer unit dealing: waves with two gMLP units no longer take a memory-attention unit; waves with one gMLP unit take two (balances per-wave work)
# baseline (speedup 1.0000x reference)
.LBB0_214:
	s_waitcnt vmcnt(0)
	v_lshlrev_b64 v[6:7], 11, v[144:145]
	s_cmpk_eq_u32 s52, 0x800
	s_cbranch_scc1 .Lmixa_rebal
	s_add_i32 s49, s49, s52
	s_add_i32 s48, s48, s52
	s_cmpk_gt_i32 s49, 0x13ff
	s_branch .Lmixa_join
.Lmixa_rebal:
	s_lshr_b32 s2, s49, 10
	s_movk_i32 s3, 0x400
	s_cmpk_lt_i32 s49, 0x800
	s_cselect_b32 s3, 0x800, s3
	s_add_i32 s49, s49, s3
	s_add_i32 s48, s48, s3
	s_cmp_eq_u32 s2, 2
	s_cselect_b32 s3, 1, 0
	s_cmp_ge_u32 s2, 4
	s_cselect_b32 s2, 1, 0
	s_or_b32 s2, s2, s3
.Lmixa_join:
	v_lshl_add_u64 v[4:5], v[4:5], 0, v[6:7]
	s_waitcnt lgkmcnt(0)
	global_store_dwordx4 v[4:5], v[0:3], off sc1
	s_cbranch_scc1 .LBB0_229
